# attention: discarded loads after a prompt item's second barrier warm the XCD L2 with the next prompt item's K/V tiles and the sample item's cache rows
# baseline (speedup 1.0000x reference)
; __device__ __forceinline__ int crow(int reg, int h) { return (reg & 3) + 8 * (reg >> 2) + 4 * h; }
; __device__ __forceinline__ void attn_prompt_wave(const Params& P, int l, int qt, int tid_in) {
;     ...
;     bf16x8 kf[5][4];
; #pragma unroll
;     for (int kb = 0; kb < 5; ++kb) {
;         int krow_ = key0 + kb * 32 + l32; krow_ = krow_ < 0 ? 0 : krow_;
;         const bf16* kp = KB + (size_t)krow_ * 128 + kvh * 64 + h * 8;
; #pragma unroll
;         for (int kk = 0; kk < 4; ++kk) kf[kb][kk] = *(const bf16x8*)(kp + kk * 16);
;     }
;     u32x2 vfa[5][2][2], vfb[5][2][2];
; #pragma unroll
;     for (int kb = 0; kb < 5; ++kb)
; #pragma unroll
;         for (int s = 0; s < 2; ++s) {
;             int k0 = key0 + kb * 32 + 16 * s + 4 * h, k1 = k0 + 8; k0 = k0 < 0 ? 0 : k0; k1 = k1 < 0 ? 0 : k1;
; #pragma unroll
;             for (int db = 0; db < 2; ++db) {
;                 const bf16* vp = VT + ((size_t)kvh * (MP / 4) * 64 + db * 32 + l32) * 4;
;                 vfa[kb][s][db] = *(const u32x2*)(vp + (size_t)(k0 >> 2) * 256); vfb[kb][s][db] = *(const u32x2*)(vp + (size_t)(k1 >> 2) * 256);
;     ...
;             for (int i = 0; i < 16; ++i) { const int ki = key0 + kb * 32 + crow(i, h); const bool ok = ki <= qi && ki > qi - 128 && ki >= bstart;
;                 st[kb][i] = ok ? st[kb][i] : -1e30f; mx = fmaxf(mx, st[kb][i]); }
.LBB0_1022:
	v_mul_hi_i32 v162, v182, s71
	v_lshrrev_b32_e32 v163, 31, v162
	v_ashrrev_i32_e32 v162, 7, v162
	v_add_u32_e32 v162, v162, v163
	v_add_u32_e32 v190, 0xffffff80, v182
	v_mul_lo_u32 v185, v162, s73
	v_cmp_le_i32_e32 vcc, v183, v182
	v_cmp_gt_i32_e64 s[36:37], v183, v190
	s_and_b64 s[0:1], vcc, s[36:37]
	v_cmp_ge_i32_e32 vcc, v183, v185
	s_and_b64 vcc, s[0:1], vcc
	v_cmp_ge_i32_e64 s[36:37], v183, v190
	v_cndmask_b32_e32 v184, v233, v0, vcc
	v_or_b32_e32 v0, 1, v183
	v_cmp_ge_i32_e64 s[38:39], v0, v185
	v_cmp_lt_i32_e32 vcc, v183, v182
	s_and_b64 s[0:1], s[36:37], s[38:39]
	s_and_b64 vcc, s[0:1], vcc
	v_cndmask_b32_e32 v171, v233, v1, vcc
	v_or_b32_e32 v1, 2, v183
	v_cmp_le_i32_e32 vcc, v1, v182
	v_cmp_gt_i32_e64 s[36:37], v1, v190
	s_and_b64 s[0:1], vcc, s[36:37]
	v_cmp_ge_i32_e32 vcc, v1, v185
	s_and_b64 vcc, s[0:1], vcc
	v_or_b32_e32 v1, 3, v183
	v_cndmask_b32_e32 v177, v233, v2, vcc
	v_cmp_le_i32_e32 vcc, v1, v182
	v_cmp_gt_i32_e64 s[36:37], v1, v190
	s_and_b64 s[0:1], vcc, s[36:37]
	v_cmp_ge_i32_e32 vcc, v1, v185
	s_and_b64 vcc, s[0:1], vcc
	v_or_b32_e32 v1, 8, v183
	v_cndmask_b32_e32 v169, v233, v3, vcc
	v_cmp_le_i32_e32 vcc, v1, v182
	v_cmp_gt_i32_e64 s[36:37], v1, v190
	s_and_b64 s[0:1], vcc, s[36:37]
	v_cmp_ge_i32_e32 vcc, v1, v185
	s_and_b64 vcc, s[0:1], vcc
	v_or_b32_e32 v1, 9, v183
	v_cndmask_b32_e32 v176, v233, v4, vcc
	v_cmp_le_i32_e32 vcc, v1, v182
	v_cmp_gt_i32_e64 s[36:37], v1, v190
	s_and_b64 s[0:1], vcc, s[36:37]
	v_cmp_ge_i32_e32 vcc, v1, v185
	s_and_b64 vcc, s[0:1], vcc
	v_or_b32_e32 v1, 10, v183
	v_cndmask_b32_e32 v168, v233, v5, vcc
	v_cmp_le_i32_e32 vcc, v1, v182
	v_cmp_gt_i32_e64 s[36:37], v1, v190
	s_and_b64 s[0:1], vcc, s[36:37]
	v_cmp_ge_i32_e32 vcc, v1, v185
	s_and_b64 vcc, s[0:1], vcc
	v_or_b32_e32 v1, 11, v183
	v_cndmask_b32_e32 v175, v233, v6, vcc
	v_cmp_le_i32_e32 vcc, v1, v182
	v_cmp_gt_i32_e64 s[36:37], v1, v190
	s_and_b64 s[0:1], vcc, s[36:37]
	v_cmp_ge_i32_e32 vcc, v1, v185
	s_and_b64 vcc, s[0:1], vcc
	v_or_b32_e32 v1, 16, v183
	v_cndmask_b32_e32 v167, v233, v7, vcc
	v_cmp_le_i32_e32 vcc, v1, v182
	v_cmp_gt_i32_e64 s[36:37], v1, v190
	s_and_b64 s[0:1], vcc, s[36:37]
	v_cmp_ge_i32_e32 vcc, v1, v185
	s_and_b64 vcc, s[0:1], vcc
	v_or_b32_e32 v1, 17, v183
	v_cndmask_b32_e32 v174, v233, v8, vcc
	v_cmp_le_i32_e32 vcc, v1, v182
	v_cmp_gt_i32_e64 s[36:37], v1, v190
	s_and_b64 s[0:1], vcc, s[36:37]
	v_cmp_ge_i32_e32 vcc, v1, v185
	s_and_b64 vcc, s[0:1], vcc
	v_or_b32_e32 v1, 18, v183
	v_cndmask_b32_e32 v165, v233, v9, vcc
	v_cmp_le_i32_e32 vcc, v1, v182
	v_cmp_gt_i32_e64 s[36:37], v1, v190
	s_and_b64 s[0:1], vcc, s[36:37]
	v_cmp_ge_i32_e32 vcc, v1, v185
	s_and_b64 vcc, s[0:1], vcc
	v_or_b32_e32 v1, 19, v183
	v_cndmask_b32_e32 v173, v233, v10, vcc
	v_cmp_le_i32_e32 vcc, v1, v182
	v_cmp_gt_i32_e64 s[36:37], v1, v190
	s_and_b64 s[0:1], vcc, s[36:37]
	v_cmp_ge_i32_e32 vcc, v1, v185
	s_and_b64 vcc, s[0:1], vcc
	v_or_b32_e32 v1, 24, v183
	v_cndmask_b32_e32 v164, v233, v11, vcc
	v_cmp_le_i32_e32 vcc, v1, v182
	v_cmp_gt_i32_e64 s[36:37], v1, v190
	s_and_b64 s[0:1], vcc, s[36:37]
	v_cmp_ge_i32_e32 vcc, v1, v185
	s_and_b64 vcc, s[0:1], vcc
	v_or_b32_e32 v1, 25, v183
	v_cndmask_b32_e32 v172, v233, v12, vcc
	v_cmp_le_i32_e32 vcc, v1, v182
	v_cmp_gt_i32_e64 s[36:37], v1, v190
	s_and_b64 s[0:1], vcc, s[36:37]
	v_cmp_ge_i32_e32 vcc, v1, v185
	s_and_b64 vcc, s[0:1], vcc
	v_or_b32_e32 v1, 26, v183
	s_waitcnt vmcnt(0) lgkmcnt(0)
	s_barrier
	s_add_i32 s15, s14, 0x100
	s_cmpk_gt_i32 s15, 0x203
	s_cbranch_scc1 .Lwarm_no_prompt
	v_readlane_b32 s16, v254, 0
	v_readlane_b32 s17, v254, 1
	v_readlane_b32 s18, v254, 2
	v_readlane_b32 s19, v254, 3
	v_and_b32_e32 v200, 7, v216
	v_bfe_u32 v201, v216, 3, 5
	v_ashrrev_i32_e32 v202, 8, v216
	v_lshlrev_b32_e32 v200, 4, v200
	s_lshl_b32 s20, s15, 5
	v_lshl_or_b32 v200, v202, 7, v200
	s_addk_i32 s20, 0xff80
	v_add_u32_e32 v201, s20, v201
	v_bfe_u32 v203, v216, 5, 3
	v_and_b32_e32 v208, 31, v216
	v_lshl_add_u32 v201, v201, 8, v200
	v_lshlrev_b32_e32 v208, 4, v208
	v_mul_u32_u24_e32 v209, 0x218000, v202
	s_lshl_b32 s21, s15, 3
	v_add_u32_e32 v208, v208, v209
	s_sub_i32 s21, s21, 32
	v_add_u32_e32 v203, s21, v203
	v_lshl_add_u32 v203, v203, 9, v208
	global_load_dwordx4 v[204:207], v201, s[16:17]
	global_load_dwordx4 v[204:207], v203, s[18:19]
	v_add_u32_e32 v201, 0x2000, v201
	v_add_u32_e32 v203, 0x1000, v203
	global_load_dwordx4 v[204:207], v201, s[16:17]
	global_load_dwordx4 v[204:207], v203, s[18:19]
	v_add_u32_e32 v201, 0x2000, v201
	v_add_u32_e32 v203, 0x1000, v203
	global_load_dwordx4 v[204:207], v201, s[16:17]
	global_load_dwordx4 v[204:207], v203, s[18:19]
	v_add_u32_e32 v201, 0x2000, v201
	v_add_u32_e32 v203, 0x1000, v203
	global_load_dwordx4 v[204:207], v201, s[16:17]
	global_load_dwordx4 v[204:207], v203, s[18:19]
	v_add_u32_e32 v201, 0x2000, v201
	v_add_u32_e32 v203, 0x1000, v203
	global_load_dwordx4 v[204:207], v201, s[16:17]
	global_load_dwordx4 v[204:207], v203, s[18:19]
; __device__ __forceinline__ int crow(int reg, int h) { return (reg & 3) + 8 * (reg >> 2) + 4 * h; }
; __device__ __forceinline__ void attn_prompt_wave(const Params& P, int l, int qt, int tid_in) {
;     ...
;     for (int kb = 0; kb < 5; ++kb) {
;         if (kb >= 1 && kb <= 3 && interior) {
; #pragma unroll
;             for (int i = 0; i < 16; ++i) mx = fmaxf(mx, st[kb][i]);
;         } else {
; #pragma unroll
;             for (int i = 0; i < 16; ++i) { const int ki = key0 + kb * 32 + crow(i, h); const bool ok = ki <= qi && ki > qi - 128 && ki >= bstart;
;                 st[kb][i] = ok ? st[kb][i] : -1e30f; mx = fmaxf(mx, st[kb][i]); }
; __device__ __forceinline__ void attn_sample_item(const Params& P, LAS unsigned char* lds, int l, int db, int kvh, int tid_in) {
;     ...
; #pragma unroll
;     for (int k = 0; k < 5; ++k) {
;         const int e = tid + 512 * k;
;         if (e < 132 * 16) {
;             const int key = e >> 4, d4 = (e & 15) * 4;
;             f32x4 kv, vv;
;             if (key < 128) { kv = *(const f32x4*)(P.in[I_CK] + ((cbase + key) * 2 + kvh) * 64 + d4); vv = *(const f32x4*)(P.in[I_CV] + ((cbase + key) * 2 + kvh) * 64 + d4); }
.Lwarm_no_prompt:
	s_cmpk_lt_i32 s14, 0x100
	s_cbranch_scc0 .Lwarm_done
	s_add_i32 s15, s14, 0xfffffffc
	s_cmp_lt_i32 s15, 0
	s_cbranch_scc1 .Lwarm_done
	s_lshr_b32 s16, s15, 1
	s_and_b32 s17, s14, 1
	s_add_i32 s16, s16, s12
	s_lshl_b32 s16, s16, 7
	s_lshl_b32 s17, s17, 8
	v_lshlrev_b32_e32 v200, 2, v216
	v_and_b32_e32 v200, 60, v200
	v_lshlrev_b32_e32 v200, 2, v200
	v_lshrrev_b32_e32 v201, 4, v216
	v_add_u32_e32 v201, s16, v201
	v_lshlrev_b32_e32 v201, 9, v201
	v_add3_u32 v201, v201, s17, v200
	v_readlane_b32 s18, v252, 29
	v_readlane_b32 s19, v252, 30
	v_readlane_b32 s20, v252, 31
	v_readlane_b32 s21, v252, 32
	s_nop 4
	global_load_dwordx4 v[204:207], v201, s[18:19]
	global_load_dwordx4 v[204:207], v201, s[20:21]
	v_add_u32_e32 v201, 0x4000, v201
	global_load_dwordx4 v[204:207], v201, s[18:19]
	global_load_dwordx4 v[204:207], v201, s[20:21]
	v_add_u32_e32 v201, 0x4000, v201
	global_load_dwordx4 v[204:207], v201, s[18:19]
	global_load_dwordx4 v[204:207], v201, s[20:21]
	v_add_u32_e32 v201, 0x4000, v201
	global_load_dwordx4 v[204:207], v201, s[18:19]
	global_load_dwordx4 v[204:207], v201, s[20:21]
.Lwarm_done:
	v_max3_f32 v0, v166, v184, v171
	v_cndmask_b32_e32 v163, v233, v13, vcc
	v_cmp_le_i32_e32 vcc, v1, v182
	v_cmp_gt_i32_e64 s[36:37], v1, v190
	v_max3_f32 v0, v0, v177, v169
	s_and_b64 s[0:1], vcc, s[36:37]
	v_cmp_ge_i32_e32 vcc, v1, v185
	v_max3_f32 v0, v0, v176, v168
	s_and_b64 vcc, s[0:1], vcc
	v_or_b32_e32 v1, 27, v183
	v_max3_f32 v0, v0, v175, v167
	v_cndmask_b32_e32 v170, v233, v14, vcc
	v_cmp_le_i32_e32 vcc, v1, v182
	v_cmp_gt_i32_e64 s[36:37], v1, v190
	v_max3_f32 v0, v0, v174, v165
	s_and_b64 s[0:1], vcc, s[36:37]
	v_cmp_ge_i32_e32 vcc, v1, v185
	v_max3_f32 v0, v0, v173, v164
	s_and_b64 vcc, s[0:1], vcc
	v_max3_f32 v0, v0, v172, v163
	v_cndmask_b32_e32 v162, v233, v15, vcc
	s_mov_b64 s[4:5], -1
	v_max3_f32 v191, v0, v170, v162
	s_and_b64 vcc, exec, s[2:3]
	s_cbranch_vccnz .LBB0_1024
	v_add_u32_e32 v15, 32, v183
	v_cmp_le_i32_e32 vcc, v15, v182
	v_cmp_gt_i32_e64 s[36:37], v15, v190
	s_and_b64 s[0:1], vcc, s[36:37]
	v_cmp_ge_i32_e32 vcc, v15, v185
	v_or_b32_e32 v1, 1, v15
	s_and_b64 vcc, s[0:1], vcc
	v_cmp_ge_i32_e64 s[36:37], v15, v190
	v_cmp_ge_i32_e64 s[38:39], v1, v185
	v_cndmask_b32_e32 v0, v233, v16, vcc
	v_cmp_lt_i32_e32 vcc, v15, v182
	s_and_b64 s[0:1], s[36:37], s[38:39]
	s_and_b64 vcc, s[0:1], vcc
	v_or_b32_e32 v2, 2, v15
	v_cndmask_b32_e32 v1, v233, v17, vcc
	v_cmp_le_i32_e32 vcc, v2, v182
	v_cmp_gt_i32_e64 s[36:37], v2, v190
	s_and_b64 s[0:1], vcc, s[36:37]
	v_cmp_ge_i32_e32 vcc, v2, v185
	s_and_b64 vcc, s[0:1], vcc
	v_or_b32_e32 v3, 3, v15
	v_cndmask_b32_e32 v2, v233, v18, vcc
	v_cmp_le_i32_e32 vcc, v3, v182
	v_cmp_gt_i32_e64 s[36:37], v3, v190
	s_and_b64 s[0:1], vcc, s[36:37]
	v_cmp_ge_i32_e32 vcc, v3, v185
	s_and_b64 vcc, s[0:1], vcc
	v_max3_f32 v4, v191, v0, v1
	v_cndmask_b32_e32 v3, v233, v19, vcc
	v_max3_f32 v6, v4, v2, v3
	v_or_b32_e32 v4, 8, v15
	v_cmp_le_i32_e32 vcc, v4, v182
	v_cmp_gt_i32_e64 s[36:37], v4, v190
	s_and_b64 s[0:1], vcc, s[36:37]
	v_cmp_ge_i32_e32 vcc, v4, v185
	s_and_b64 vcc, s[0:1], vcc
	v_or_b32_e32 v5, 9, v15
	v_cndmask_b32_e32 v4, v233, v20, vcc
	v_cmp_le_i32_e32 vcc, v5, v182
	v_cmp_gt_i32_e64 s[36:37], v5, v190
	s_and_b64 s[0:1], vcc, s[36:37]
	v_cmp_ge_i32_e32 vcc, v5, v185
	s_and_b64 vcc, s[0:1], vcc
	v_or_b32_e32 v7, 11, v15
	v_cndmask_b32_e32 v5, v233, v21, vcc
	v_max3_f32 v8, v6, v4, v5
	v_or_b32_e32 v6, 10, v15
	v_cmp_le_i32_e32 vcc, v6, v182
	v_cmp_gt_i32_e64 s[36:37], v6, v190
	s_and_b64 s[0:1], vcc, s[36:37]
	v_cmp_ge_i32_e32 vcc, v6, v185
	s_and_b64 vcc, s[0:1], vcc
	v_cmp_gt_i32_e64 s[36:37], v7, v190
	v_cndmask_b32_e32 v6, v233, v22, vcc
	v_cmp_le_i32_e32 vcc, v7, v182
	s_and_b64 s[0:1], vcc, s[36:37]
	v_cmp_ge_i32_e32 vcc, v7, v185
	s_and_b64 vcc, s[0:1], vcc
	v_or_b32_e32 v9, 17, v15
	v_cndmask_b32_e32 v7, v233, v23, vcc
	v_max3_f32 v10, v8, v6, v7
	v_or_b32_e32 v8, 16, v15
	v_cmp_le_i32_e32 vcc, v8, v182
	v_cmp_gt_i32_e64 s[36:37], v8, v190
	s_and_b64 s[0:1], vcc, s[36:37]
	v_cmp_ge_i32_e32 vcc, v8, v185
	s_and_b64 vcc, s[0:1], vcc
	v_cmp_gt_i32_e64 s[36:37], v9, v190
	v_cndmask_b32_e32 v8, v233, v24, vcc
	v_cmp_le_i32_e32 vcc, v9, v182
	s_and_b64 s[0:1], vcc, s[36:37]
	v_cmp_ge_i32_e32 vcc, v9, v185
	s_and_b64 vcc, s[0:1], vcc
	v_or_b32_e32 v11, 19, v15
	v_cndmask_b32_e32 v9, v233, v25, vcc
	v_max3_f32 v12, v10, v8, v9
	v_or_b32_e32 v10, 18, v15
	v_cmp_le_i32_e32 vcc, v10, v182
	v_cmp_gt_i32_e64 s[36:37], v10, v190
	s_and_b64 s[0:1], vcc, s[36:37]
	v_cmp_ge_i32_e32 vcc, v10, v185
	s_and_b64 vcc, s[0:1], vcc
	v_cmp_gt_i32_e64 s[36:37], v11, v190
	v_cndmask_b32_e32 v10, v233, v26, vcc
	v_cmp_le_i32_e32 vcc, v11, v182
	s_and_b64 s[0:1], vcc, s[36:37]
	v_cmp_ge_i32_e32 vcc, v11, v185
	s_and_b64 vcc, s[0:1], vcc
	v_or_b32_e32 v13, 25, v15
	v_cndmask_b32_e32 v11, v233, v27, vcc
	v_max3_f32 v14, v12, v10, v11
	v_or_b32_e32 v12, 24, v15
	v_cmp_le_i32_e32 vcc, v12, v182
	v_cmp_gt_i32_e64 s[36:37], v12, v190
	s_and_b64 s[0:1], vcc, s[36:37]
	v_cmp_ge_i32_e32 vcc, v12, v185
	s_and_b64 vcc, s[0:1], vcc
	v_cmp_gt_i32_e64 s[36:37], v13, v190
	v_cndmask_b32_e32 v12, v233, v28, vcc
	v_cmp_le_i32_e32 vcc, v13, v182
	s_and_b64 s[0:1], vcc, s[36:37]
	v_cmp_ge_i32_e32 vcc, v13, v185
	s_and_b64 vcc, s[0:1], vcc
	s_mov_b64 s[4:5], 0
	v_cndmask_b32_e32 v13, v233, v29, vcc
	v_max3_f32 v186, v14, v12, v13
	v_or_b32_e32 v14, 26, v15
	v_cmp_le_i32_e32 vcc, v14, v182
	v_cmp_gt_i32_e64 s[36:37], v14, v190
	s_and_b64 s[0:1], vcc, s[36:37]
	v_cmp_ge_i32_e32 vcc, v14, v185
	s_and_b64 vcc, s[0:1], vcc
	v_or_b32_e32 v15, 27, v15
	v_cndmask_b32_e32 v14, v233, v30, vcc
	v_cmp_le_i32_e32 vcc, v15, v182
	v_cmp_gt_i32_e64 s[36:37], v15, v190
	s_and_b64 s[0:1], vcc, s[36:37]
	v_cmp_ge_i32_e32 vcc, v15, v185
	s_and_b64 vcc, s[0:1], vcc
	s_nop 0
	v_cndmask_b32_e32 v15, v233, v31, vcc
	v_max3_f32 v192, v186, v14, v15
